# v20 + P2a (RWKV pre-phase) output stores write-through (sc0 sc1) so the grid barrier's L2 write-back has little left to flush
# baseline (speedup 1.0000x reference)
.LBB0_228:
	s_andn2_saveexec_b64 s[2:3], s[4:5]
	s_or_b64 exec, exec, s[2:3]
	s_waitcnt vmcnt(0)
	v_add_f32_e32 v28, v190, v28
	v_mul_f32_e32 v28, 0xbfb8aa3b, v28
	v_exp_f32_e32 v28, v28
	v_lshl_add_u32 v116, v182, 2, s28
	v_subrev_u32_e32 v120, 51, v116
	v_ashrrev_i32_e32 v121, 31, v120
	v_add_f32_e32 v28, 1.0, v28
	v_rcp_f32_e32 v28, v28
	v_lshl_add_u64 v[184:185], v[0:1], 1, s[20:21]
	v_lshlrev_b64 v[138:139], 9, v[120:121]
	v_lshl_add_u64 v[36:37], v[184:185], 0, v[138:139]
	v_cvt_pk_bf16_f32 v28, v28, s0
	global_store_short v[36:37], v28, off sc0 sc1
	v_add_f32_e32 v28, v2, v33
	v_cmp_ngt_f32_e32 vcc, s74, v28
	v_xor_b32_e32 v206, 0x80000000, v28
	s_and_saveexec_b64 s[2:3], vcc
	s_xor_b64 s[4:5], exec, s[2:3]
	s_cbranch_execz .LBB0_230
	v_mul_f32_e32 v28, 0xbfb8aa3b, v28
	v_exp_f32_e32 v28, v28
	s_nop 0
	v_add_f32_e32 v28, 1.0, v28
	v_cmp_gt_f32_e32 vcc, s75, v28
	s_nop 1
	v_cndmask_b32_e64 v32, 0, 32, vcc
	v_ldexp_f32 v28, v28, v32
	v_log_f32_e32 v28, v28
	s_nop 0
	v_mul_f32_e32 v32, 0x3f317217, v28
	v_fma_f32 v32, v28, s88, -v32
	v_fmac_f32_e32 v32, 0x3377d1cf, v28
	v_fmac_f32_e32 v32, 0x3f317217, v28
	v_cmp_lt_f32_e64 s[2:3], |v28|, s70
	s_nop 1
	v_cndmask_b32_e64 v28, v28, v32, s[2:3]
	v_cndmask_b32_e32 v32, 0, v233, vcc
	v_sub_f32_e32 v206, v28, v32
.LBB0_230:
	s_andn2_saveexec_b64 s[2:3], s[4:5]
	s_or_b64 exec, exec, s[2:3]
	v_add_f32_e32 v28, v190, v29
	v_mul_f32_e32 v28, 0xbfb8aa3b, v28
	v_exp_f32_e32 v28, v28
	v_subrev_u32_e32 v186, 50, v116
	v_ashrrev_i32_e32 v187, 31, v186
	v_lshlrev_b64 v[142:143], 9, v[186:187]
	v_add_f32_e32 v28, 1.0, v28
	v_rcp_f32_e32 v28, v28
	s_nop 0
	v_cvt_pk_bf16_f32 v32, v28, s0
	v_lshl_add_u64 v[28:29], v[184:185], 0, v[142:143]
	global_store_short v[28:29], v32, off sc0 sc1
	v_add_f32_e32 v28, v2, v34
	v_cmp_ngt_f32_e32 vcc, s74, v28
	v_xor_b32_e32 v207, 0x80000000, v28
	s_and_saveexec_b64 s[2:3], vcc
	s_xor_b64 s[4:5], exec, s[2:3]
	s_cbranch_execz .LBB0_232
	v_mul_f32_e32 v28, 0xbfb8aa3b, v28
	v_exp_f32_e32 v28, v28
	s_nop 0
	v_add_f32_e32 v28, 1.0, v28
	v_cmp_gt_f32_e32 vcc, s75, v28
	s_nop 1
	v_cndmask_b32_e64 v29, 0, 32, vcc
	v_ldexp_f32 v28, v28, v29
	v_log_f32_e32 v28, v28
	s_nop 0
	v_mul_f32_e32 v29, 0x3f317217, v28
	v_fma_f32 v29, v28, s88, -v29
	v_fmac_f32_e32 v29, 0x3377d1cf, v28
	v_fmac_f32_e32 v29, 0x3f317217, v28
	v_cmp_lt_f32_e64 s[2:3], |v28|, s70
	s_nop 1
	v_cndmask_b32_e64 v28, v28, v29, s[2:3]
	v_cndmask_b32_e32 v29, 0, v233, vcc
	v_sub_f32_e32 v207, v28, v29
.LBB0_232:
	s_andn2_saveexec_b64 s[2:3], s[4:5]
	s_or_b64 exec, exec, s[2:3]
	v_add_f32_e32 v28, v190, v30
	v_mul_f32_e32 v28, 0xbfb8aa3b, v28
	v_exp_f32_e32 v29, v28
	v_subrev_u32_e32 v188, 49, v116
	v_ashrrev_i32_e32 v189, 31, v188
	v_add_f32_e32 v28, v2, v35
	v_add_f32_e32 v29, 1.0, v29
	v_rcp_f32_e32 v29, v29
	v_lshlrev_b64 v[146:147], 9, v[188:189]
	v_cmp_ngt_f32_e32 vcc, s74, v28
	v_lshl_add_u64 v[32:33], v[184:185], 0, v[146:147]
	v_cvt_pk_bf16_f32 v29, v29, s0
	v_xor_b32_e32 v208, 0x80000000, v28
	global_store_short v[32:33], v29, off sc0 sc1
	s_and_saveexec_b64 s[2:3], vcc
	s_xor_b64 s[4:5], exec, s[2:3]
	s_cbranch_execz .LBB0_234
	v_mul_f32_e32 v28, 0xbfb8aa3b, v28
	v_exp_f32_e32 v28, v28
	s_nop 0
	v_add_f32_e32 v28, 1.0, v28
	v_cmp_gt_f32_e32 vcc, s75, v28
	s_nop 1
	v_cndmask_b32_e64 v29, 0, 32, vcc
	v_ldexp_f32 v28, v28, v29
	v_log_f32_e32 v28, v28
	s_nop 0
	v_mul_f32_e32 v29, 0x3f317217, v28
	v_fma_f32 v29, v28, s88, -v29
	v_fmac_f32_e32 v29, 0x3377d1cf, v28
	v_fmac_f32_e32 v29, 0x3f317217, v28
	v_cmp_lt_f32_e64 s[2:3], |v28|, s70
	s_nop 1
	v_cndmask_b32_e64 v28, v28, v29, s[2:3]
	v_cndmask_b32_e32 v29, 0, v233, vcc
	v_sub_f32_e32 v208, v28, v29
.LBB0_234:
	s_andn2_saveexec_b64 s[2:3], s[4:5]
	s_or_b64 exec, exec, s[2:3]
	v_add_f32_e32 v28, v190, v31
	v_mul_f32_e32 v28, 0xbfb8aa3b, v28
	v_exp_f32_e32 v28, v28
	v_subrev_u32_e32 v192, 48, v116
	v_ashrrev_i32_e32 v193, 31, v192
	v_lshlrev_b64 v[144:145], 9, v[192:193]
	v_add_f32_e32 v28, 1.0, v28
	v_rcp_f32_e32 v28, v28
	s_nop 0
	v_cvt_pk_bf16_f32 v30, v28, s0
	v_lshl_add_u64 v[28:29], v[184:185], 0, v[144:145]
	global_store_short v[28:29], v30, off sc0 sc1
	ds_read_b128 v[40:43], v174 offset:2304
	ds_read_b128 v[44:47], v174 offset:11520
	ds_read_b128 v[32:35], v174 offset:20736
	s_waitcnt lgkmcnt(2)
	v_mfma_f32_16x16x32_bf16 v[28:31], v[40:43], v[76:79], 0
	s_waitcnt lgkmcnt(1)
	v_mfma_f32_16x16x32_bf16 v[28:31], v[44:47], v[76:79], v[28:31]
	v_mfma_f32_16x16x32_bf16 v[52:55], v[40:43], v[96:99], v[28:31]
	s_nop 6
	ds_read_b128 v[28:31], v174 offset:2368
	ds_read_b128 v[48:51], v174 offset:11584
	ds_read_b128 v[36:39], v174 offset:20800
	s_waitcnt lgkmcnt(2)
	v_mfma_f32_16x16x32_bf16 v[52:55], v[28:31], v[108:111], v[52:55]
	s_waitcnt lgkmcnt(1)
	v_mfma_f32_16x16x32_bf16 v[52:55], v[48:51], v[108:111], v[52:55]
	v_mfma_f32_16x16x32_bf16 v[60:63], v[32:35], v[88:91], 0
	v_mfma_f32_16x16x32_bf16 v[56:59], v[28:31], v[104:107], v[52:55]
	s_waitcnt lgkmcnt(0)
	v_mfma_f32_16x16x32_bf16 v[52:55], v[36:39], v[100:103], v[60:63]
	s_nop 5
	v_add_f32_e32 v56, v2, v56
	v_cmp_ngt_f32_e32 vcc, s74, v56
	v_xor_b32_e32 v209, 0x80000000, v56
	s_and_saveexec_b64 s[2:3], vcc
	s_xor_b64 s[4:5], exec, s[2:3]
	s_cbranch_execz .LBB0_236
	v_mul_f32_e32 v56, 0xbfb8aa3b, v56
	v_exp_f32_e32 v56, v56
	s_nop 0
	v_add_f32_e32 v56, 1.0, v56
	v_cmp_gt_f32_e32 vcc, s75, v56
	s_nop 1
	v_cndmask_b32_e64 v60, 0, 32, vcc
	v_ldexp_f32 v56, v56, v60
	v_log_f32_e32 v56, v56
	s_nop 0
	v_mul_f32_e32 v60, 0x3f317217, v56
	v_fma_f32 v60, v56, s88, -v60
	v_fmac_f32_e32 v60, 0x3377d1cf, v56
	v_fmac_f32_e32 v60, 0x3f317217, v56
	v_cmp_lt_f32_e64 s[2:3], |v56|, s70
	s_nop 1
	v_cndmask_b32_e64 v56, v56, v60, s[2:3]
	v_cndmask_b32_e32 v60, 0, v233, vcc
	v_sub_f32_e32 v209, v56, v60
.LBB0_236:
	s_andn2_saveexec_b64 s[2:3], s[4:5]
	s_or_b64 exec, exec, s[2:3]
	v_add_f32_e32 v52, v190, v52
	v_mul_f32_e32 v52, 0xbfb8aa3b, v52
	v_exp_f32_e32 v52, v52
	v_subrev_u32_e32 v194, 35, v116
	v_ashrrev_i32_e32 v195, 31, v194
	v_lshlrev_b64 v[148:149], 9, v[194:195]
	v_add_f32_e32 v52, 1.0, v52
	v_rcp_f32_e32 v52, v52
	v_lshl_add_u64 v[60:61], v[184:185], 0, v[148:149]
	v_cvt_pk_bf16_f32 v52, v52, s0
	global_store_short v[60:61], v52, off sc0 sc1
	v_add_f32_e32 v52, v2, v57
	v_cmp_ngt_f32_e32 vcc, s74, v52
	v_xor_b32_e32 v210, 0x80000000, v52
	s_and_saveexec_b64 s[2:3], vcc
	s_xor_b64 s[4:5], exec, s[2:3]
	s_cbranch_execz .LBB0_238
	v_mul_f32_e32 v52, 0xbfb8aa3b, v52
	v_exp_f32_e32 v52, v52
	s_nop 0
	v_add_f32_e32 v52, 1.0, v52
	v_cmp_gt_f32_e32 vcc, s75, v52
	s_nop 1
	v_cndmask_b32_e64 v56, 0, 32, vcc
	v_ldexp_f32 v52, v52, v56
	v_log_f32_e32 v52, v52
	s_nop 0
	v_mul_f32_e32 v56, 0x3f317217, v52
	v_fma_f32 v56, v52, s88, -v56
	v_fmac_f32_e32 v56, 0x3377d1cf, v52
	v_fmac_f32_e32 v56, 0x3f317217, v52
	v_cmp_lt_f32_e64 s[2:3], |v52|, s70
	s_nop 1
	v_cndmask_b32_e64 v52, v52, v56, s[2:3]
	v_cndmask_b32_e32 v56, 0, v233, vcc
	v_sub_f32_e32 v210, v52, v56
.LBB0_238:
	s_andn2_saveexec_b64 s[2:3], s[4:5]
	s_or_b64 exec, exec, s[2:3]
	v_add_f32_e32 v52, v190, v53
	v_mul_f32_e32 v52, 0xbfb8aa3b, v52
	v_exp_f32_e32 v52, v52
	v_subrev_u32_e32 v196, 34, v116
	v_ashrrev_i32_e32 v197, 31, v196
	v_lshlrev_b64 v[150:151], 9, v[196:197]
	v_add_f32_e32 v52, 1.0, v52
	v_rcp_f32_e32 v52, v52
	s_nop 0
	v_cvt_pk_bf16_f32 v56, v52, s0
	v_lshl_add_u64 v[52:53], v[184:185], 0, v[150:151]
	global_store_short v[52:53], v56, off sc0 sc1
	v_add_f32_e32 v52, v2, v58
	v_cmp_ngt_f32_e32 vcc, s74, v52
	v_xor_b32_e32 v211, 0x80000000, v52
	s_and_saveexec_b64 s[2:3], vcc
	s_xor_b64 s[4:5], exec, s[2:3]
	s_cbranch_execz .LBB0_240
	v_mul_f32_e32 v52, 0xbfb8aa3b, v52
	v_exp_f32_e32 v52, v52
	s_nop 0
	v_add_f32_e32 v52, 1.0, v52
	v_cmp_gt_f32_e32 vcc, s75, v52
	s_nop 1
	v_cndmask_b32_e64 v53, 0, 32, vcc
	v_ldexp_f32 v52, v52, v53
	v_log_f32_e32 v52, v52
	s_nop 0
	v_mul_f32_e32 v53, 0x3f317217, v52
	v_fma_f32 v53, v52, s88, -v53
	v_fmac_f32_e32 v53, 0x3377d1cf, v52
	v_fmac_f32_e32 v53, 0x3f317217, v52
	v_cmp_lt_f32_e64 s[2:3], |v52|, s70
	s_nop 1
	v_cndmask_b32_e64 v52, v52, v53, s[2:3]
	v_cndmask_b32_e32 v53, 0, v233, vcc
	v_sub_f32_e32 v211, v52, v53
.LBB0_240:
	s_andn2_saveexec_b64 s[2:3], s[4:5]
	s_or_b64 exec, exec, s[2:3]
	v_add_f32_e32 v52, v190, v54
	v_mul_f32_e32 v52, 0xbfb8aa3b, v52
	v_exp_f32_e32 v53, v52
	v_subrev_u32_e32 v198, 33, v116
	v_ashrrev_i32_e32 v199, 31, v198
	v_add_f32_e32 v52, v2, v59
	v_add_f32_e32 v53, 1.0, v53
	v_rcp_f32_e32 v53, v53
	v_lshlrev_b64 v[154:155], 9, v[198:199]
	v_cmp_ngt_f32_e32 vcc, s74, v52
	v_lshl_add_u64 v[56:57], v[184:185], 0, v[154:155]
	v_cvt_pk_bf16_f32 v53, v53, s0
	v_xor_b32_e32 v212, 0x80000000, v52
	global_store_short v[56:57], v53, off sc0 sc1
	s_and_saveexec_b64 s[2:3], vcc
	s_xor_b64 s[4:5], exec, s[2:3]
	s_cbranch_execz .LBB0_242
	v_mul_f32_e32 v52, 0xbfb8aa3b, v52
	v_exp_f32_e32 v52, v52
	s_nop 0
	v_add_f32_e32 v52, 1.0, v52
	v_cmp_gt_f32_e32 vcc, s75, v52
	s_nop 1
	v_cndmask_b32_e64 v53, 0, 32, vcc
	v_ldexp_f32 v52, v52, v53
	v_log_f32_e32 v52, v52
	s_nop 0
	v_mul_f32_e32 v53, 0x3f317217, v52
	v_fma_f32 v53, v52, s88, -v53
	v_fmac_f32_e32 v53, 0x3377d1cf, v52
	v_fmac_f32_e32 v53, 0x3f317217, v52
	v_cmp_lt_f32_e64 s[2:3], |v52|, s70
	s_nop 1
	v_cndmask_b32_e64 v52, v52, v53, s[2:3]
	v_cndmask_b32_e32 v53, 0, v233, vcc
	v_sub_f32_e32 v212, v52, v53
.LBB0_242:
	s_andn2_saveexec_b64 s[2:3], s[4:5]
	s_or_b64 exec, exec, s[2:3]
	v_add_f32_e32 v52, v190, v55
	v_mul_f32_e32 v52, 0xbfb8aa3b, v52
	v_exp_f32_e32 v52, v52
	v_subrev_u32_e32 v200, 32, v116
	v_ashrrev_i32_e32 v201, 31, v200
	v_lshlrev_b64 v[152:153], 9, v[200:201]
	v_add_f32_e32 v52, 1.0, v52
	v_rcp_f32_e32 v52, v52
	s_nop 0
	v_cvt_pk_bf16_f32 v54, v52, s0
	v_lshl_add_u64 v[52:53], v[184:185], 0, v[152:153]
	global_store_short v[52:53], v54, off sc0 sc1
	ds_read_b128 v[64:67], v174 offset:4608
	ds_read_b128 v[68:71], v174 offset:13824
	ds_read_b128 v[56:59], v174 offset:23040
	s_waitcnt lgkmcnt(2)
	v_mfma_f32_16x16x32_bf16 v[52:55], v[64:67], v[76:79], 0
	s_waitcnt lgkmcnt(1)
	v_mfma_f32_16x16x32_bf16 v[52:55], v[68:71], v[76:79], v[52:55]
	v_mfma_f32_16x16x32_bf16 v[80:83], v[64:67], v[96:99], v[52:55]
	s_nop 6
	ds_read_b128 v[52:55], v174 offset:4672
	ds_read_b128 v[72:75], v174 offset:13888
	ds_read_b128 v[60:63], v174 offset:23104
	s_waitcnt lgkmcnt(2)
	v_mfma_f32_16x16x32_bf16 v[80:83], v[52:55], v[108:111], v[80:83]
	s_waitcnt lgkmcnt(1)
	v_mfma_f32_16x16x32_bf16 v[80:83], v[72:75], v[108:111], v[80:83]
	v_mfma_f32_16x16x32_bf16 v[84:87], v[56:59], v[88:91], 0
	v_mfma_f32_16x16x32_bf16 v[80:83], v[52:55], v[104:107], v[80:83]
	s_waitcnt lgkmcnt(0)
	v_mfma_f32_16x16x32_bf16 v[112:115], v[60:63], v[100:103], v[84:87]
	s_nop 5
	v_add_f32_e32 v80, v2, v80
	v_cmp_ngt_f32_e32 vcc, s74, v80
	v_xor_b32_e32 v213, 0x80000000, v80
	s_and_saveexec_b64 s[2:3], vcc
	s_xor_b64 s[4:5], exec, s[2:3]
	s_cbranch_execz .LBB0_244
	v_mul_f32_e32 v80, 0xbfb8aa3b, v80
	v_exp_f32_e32 v80, v80
	s_nop 0
	v_add_f32_e32 v80, 1.0, v80
	v_cmp_gt_f32_e32 vcc, s75, v80
	s_nop 1
	v_cndmask_b32_e64 v84, 0, 32, vcc
	v_ldexp_f32 v80, v80, v84
	v_log_f32_e32 v80, v80
	s_nop 0
	v_mul_f32_e32 v84, 0x3f317217, v80
	v_fma_f32 v84, v80, s88, -v84
	v_fmac_f32_e32 v84, 0x3377d1cf, v80
	v_fmac_f32_e32 v84, 0x3f317217, v80
	v_cmp_lt_f32_e64 s[2:3], |v80|, s70
	s_nop 1
	v_cndmask_b32_e64 v80, v80, v84, s[2:3]
	v_cndmask_b32_e32 v84, 0, v233, vcc
	v_sub_f32_e32 v213, v80, v84
.LBB0_244:
	s_andn2_saveexec_b64 s[2:3], s[4:5]
	s_or_b64 exec, exec, s[2:3]
	v_add_f32_e32 v80, v190, v112
	v_mul_f32_e32 v80, 0xbfb8aa3b, v80
	v_exp_f32_e32 v80, v80
	v_subrev_u32_e32 v202, 19, v116
	v_ashrrev_i32_e32 v203, 31, v202
	v_lshlrev_b64 v[168:169], 9, v[202:203]
	v_add_f32_e32 v80, 1.0, v80
	v_rcp_f32_e32 v80, v80
	v_lshl_add_u64 v[84:85], v[184:185], 0, v[168:169]
	v_cvt_pk_bf16_f32 v80, v80, s0
	global_store_short v[84:85], v80, off sc0 sc1
	v_add_f32_e32 v80, v2, v81
	v_cmp_ngt_f32_e32 vcc, s74, v80
	v_xor_b32_e32 v214, 0x80000000, v80
	s_and_saveexec_b64 s[2:3], vcc
	s_xor_b64 s[4:5], exec, s[2:3]
	s_cbranch_execz .LBB0_246
	v_mul_f32_e32 v80, 0xbfb8aa3b, v80
	v_exp_f32_e32 v80, v80
	s_nop 0
	v_add_f32_e32 v80, 1.0, v80
	v_cmp_gt_f32_e32 vcc, s75, v80
	s_nop 1
	v_cndmask_b32_e64 v81, 0, 32, vcc
	v_ldexp_f32 v80, v80, v81
	v_log_f32_e32 v80, v80
	s_nop 0
	v_mul_f32_e32 v81, 0x3f317217, v80
	v_fma_f32 v81, v80, s88, -v81
	v_fmac_f32_e32 v81, 0x3377d1cf, v80
	v_fmac_f32_e32 v81, 0x3f317217, v80
	v_cmp_lt_f32_e64 s[2:3], |v80|, s70
	s_nop 1
	v_cndmask_b32_e64 v80, v80, v81, s[2:3]
	v_cndmask_b32_e32 v81, 0, v233, vcc
	v_sub_f32_e32 v214, v80, v81
.LBB0_246:
	s_andn2_saveexec_b64 s[2:3], s[4:5]
	s_or_b64 exec, exec, s[2:3]
	v_add_f32_e32 v80, v190, v113
	v_mul_f32_e32 v80, 0xbfb8aa3b, v80
	v_exp_f32_e32 v80, v80
	v_subrev_u32_e32 v112, 18, v116
	v_ashrrev_i32_e32 v113, 31, v112
	v_lshlrev_b64 v[170:171], 9, v[112:113]
	v_add_f32_e32 v80, 1.0, v80
	v_rcp_f32_e32 v80, v80
	s_nop 0
	v_cvt_pk_bf16_f32 v84, v80, s0
	v_lshl_add_u64 v[80:81], v[184:185], 0, v[170:171]
	global_store_short v[80:81], v84, off sc0 sc1
	v_add_f32_e32 v80, v2, v82
	v_cmp_ngt_f32_e32 vcc, s74, v80
	v_xor_b32_e32 v215, 0x80000000, v80
	s_and_saveexec_b64 s[2:3], vcc
	s_xor_b64 s[4:5], exec, s[2:3]
	s_cbranch_execz .LBB0_248
	v_mul_f32_e32 v80, 0xbfb8aa3b, v80
	v_exp_f32_e32 v80, v80
	s_nop 0
	v_add_f32_e32 v80, 1.0, v80
	v_cmp_gt_f32_e32 vcc, s75, v80
	s_nop 1
	v_cndmask_b32_e64 v81, 0, 32, vcc
	v_ldexp_f32 v80, v80, v81
	v_log_f32_e32 v80, v80
	s_nop 0
	v_mul_f32_e32 v81, 0x3f317217, v80
	v_fma_f32 v81, v80, s88, -v81
	v_fmac_f32_e32 v81, 0x3377d1cf, v80
	v_fmac_f32_e32 v81, 0x3f317217, v80
	v_cmp_lt_f32_e64 s[2:3], |v80|, s70
	s_nop 1
	v_cndmask_b32_e64 v80, v80, v81, s[2:3]
	v_cndmask_b32_e32 v81, 0, v233, vcc
	v_sub_f32_e32 v215, v80, v81
.LBB0_248:
	s_andn2_saveexec_b64 s[2:3], s[4:5]
	s_or_b64 exec, exec, s[2:3]
	v_add_f32_e32 v80, v190, v114
	v_mul_f32_e32 v80, 0xbfb8aa3b, v80
	v_exp_f32_e32 v81, v80
	v_subrev_u32_e32 v204, 17, v116
	v_ashrrev_i32_e32 v205, 31, v204
	v_add_f32_e32 v80, v2, v83
	v_add_f32_e32 v81, 1.0, v81
	v_rcp_f32_e32 v81, v81
	v_lshlrev_b64 v[172:173], 9, v[204:205]
	v_cmp_ngt_f32_e32 vcc, s74, v80
	v_lshl_add_u64 v[82:83], v[184:185], 0, v[172:173]
	v_cvt_pk_bf16_f32 v81, v81, s0
	v_xor_b32_e32 v244, 0x80000000, v80
	global_store_short v[82:83], v81, off sc0 sc1
	s_and_saveexec_b64 s[2:3], vcc
	s_xor_b64 s[4:5], exec, s[2:3]
	s_cbranch_execz .LBB0_250
	v_mul_f32_e32 v80, 0xbfb8aa3b, v80
	v_exp_f32_e32 v80, v80
	s_nop 0
	v_add_f32_e32 v80, 1.0, v80
	v_cmp_gt_f32_e32 vcc, s75, v80
	s_nop 1
	v_cndmask_b32_e64 v81, 0, 32, vcc
	v_ldexp_f32 v80, v80, v81
	v_log_f32_e32 v80, v80
	s_nop 0
	v_mul_f32_e32 v81, 0x3f317217, v80
	v_fma_f32 v81, v80, s88, -v81
	v_fmac_f32_e32 v81, 0x3377d1cf, v80
	v_fmac_f32_e32 v81, 0x3f317217, v80
	v_cmp_lt_f32_e64 s[2:3], |v80|, s70
	s_nop 1
	v_cndmask_b32_e64 v80, v80, v81, s[2:3]
	v_cndmask_b32_e32 v81, 0, v233, vcc
	v_sub_f32_e32 v244, v80, v81
.LBB0_250:
	s_andn2_saveexec_b64 s[2:3], s[4:5]
	s_or_b64 exec, exec, s[2:3]
	ds_read_b128 v[84:87], v174 offset:6912
	ds_read_b128 v[92:95], v174 offset:16128
	ds_read_b128 v[80:83], v174 offset:25344
	v_add_f32_e32 v115, v190, v115
	v_mul_f32_e32 v115, 0xbfb8aa3b, v115
	v_exp_f32_e32 v175, v115
	v_add_u32_e32 v114, -16, v116
	v_ashrrev_i32_e32 v115, 31, v114
	s_waitcnt lgkmcnt(2)
	v_mfma_f32_16x16x32_bf16 v[176:179], v[84:87], v[76:79], 0
	s_waitcnt lgkmcnt(1)
	v_mfma_f32_16x16x32_bf16 v[176:179], v[92:95], v[76:79], v[176:179]
	s_waitcnt lgkmcnt(0)
	v_mfma_f32_16x16x32_bf16 v[246:249], v[80:83], v[88:91], 0
	ds_read_b128 v[76:79], v174 offset:6976
	ds_read_b128 v[88:91], v174 offset:16192
	v_mfma_f32_16x16x32_bf16 v[96:99], v[84:87], v[96:99], v[176:179]
	s_waitcnt lgkmcnt(1)
	v_mfma_f32_16x16x32_bf16 v[176:179], v[76:79], v[108:111], v[96:99]
	s_waitcnt lgkmcnt(0)
	v_mfma_f32_16x16x32_bf16 v[108:111], v[88:91], v[108:111], v[176:179]
	s_nop 3
	ds_read_b128 v[96:99], v174 offset:25408
	v_add_f32_e32 v174, 1.0, v175
	v_rcp_f32_e32 v174, v174
	v_mfma_f32_16x16x32_bf16 v[104:107], v[76:79], v[104:107], v[108:111]
	v_lshlrev_b64 v[178:179], 9, v[114:115]
	s_waitcnt lgkmcnt(0)
	v_mfma_f32_16x16x32_bf16 v[100:103], v[96:99], v[100:103], v[246:249]
	v_lshl_add_u64 v[108:109], v[184:185], 0, v[178:179]
	v_cvt_pk_bf16_f32 v110, v174, s0
	s_nop 2
	v_add_f32_e32 v104, v2, v104
	global_store_short v[108:109], v110, off sc0 sc1
	v_cmp_ngt_f32_e32 vcc, s74, v104
	v_xor_b32_e32 v110, 0x80000000, v104
	s_and_saveexec_b64 s[2:3], vcc
	s_xor_b64 s[4:5], exec, s[2:3]
	s_cbranch_execz .LBB0_252
	v_mul_f32_e32 v104, 0xbfb8aa3b, v104
	v_exp_f32_e32 v104, v104
	s_nop 0
	v_add_f32_e32 v104, 1.0, v104
	v_cmp_gt_f32_e32 vcc, s75, v104
	s_nop 1
	v_cndmask_b32_e64 v108, 0, 32, vcc
	v_ldexp_f32 v104, v104, v108
	v_log_f32_e32 v104, v104
	s_nop 0
	v_mul_f32_e32 v108, 0x3f317217, v104
	v_fma_f32 v108, v104, s88, -v108
	v_fmac_f32_e32 v108, 0x3377d1cf, v104
	v_fmac_f32_e32 v108, 0x3f317217, v104
	v_cmp_lt_f32_e64 s[2:3], |v104|, s70
	s_nop 1
	v_cndmask_b32_e64 v104, v104, v108, s[2:3]
	v_cndmask_b32_e32 v108, 0, v233, vcc
	v_sub_f32_e32 v110, v104, v108
.LBB0_252:
	s_andn2_saveexec_b64 s[2:3], s[4:5]
	s_or_b64 exec, exec, s[2:3]
	v_add_f32_e32 v100, v190, v100
	v_mul_f32_e32 v100, 0xbfb8aa3b, v100
	v_exp_f32_e32 v100, v100
	v_add_u32_e32 v108, -3, v116
	v_ashrrev_i32_e32 v109, 31, v108
	v_lshlrev_b64 v[174:175], 9, v[108:109]
	v_add_f32_e32 v100, 1.0, v100
	v_rcp_f32_e32 v100, v100
	v_lshl_add_u64 v[176:177], v[184:185], 0, v[174:175]
	v_cvt_pk_bf16_f32 v100, v100, s0
	global_store_short v[176:177], v100, off sc0 sc1
	v_add_f32_e32 v100, v2, v105
	v_cmp_ngt_f32_e32 vcc, s74, v100
	v_xor_b32_e32 v111, 0x80000000, v100
	s_and_saveexec_b64 s[2:3], vcc
	s_xor_b64 s[4:5], exec, s[2:3]
	s_cbranch_execz .LBB0_254
	v_mul_f32_e32 v100, 0xbfb8aa3b, v100
	v_exp_f32_e32 v100, v100
	s_nop 0
	v_add_f32_e32 v100, 1.0, v100
	v_cmp_gt_f32_e32 vcc, s75, v100
	s_nop 1
	v_cndmask_b32_e64 v104, 0, 32, vcc
	v_ldexp_f32 v100, v100, v104
	v_log_f32_e32 v100, v100
	s_nop 0
	v_mul_f32_e32 v104, 0x3f317217, v100
	v_fma_f32 v104, v100, s88, -v104
	v_fmac_f32_e32 v104, 0x3377d1cf, v100
	v_fmac_f32_e32 v104, 0x3f317217, v100
	v_cmp_lt_f32_e64 s[2:3], |v100|, s70
	s_nop 1
	v_cndmask_b32_e64 v100, v100, v104, s[2:3]
	v_cndmask_b32_e32 v104, 0, v233, vcc
	v_sub_f32_e32 v111, v100, v104
.LBB0_254:
	s_andn2_saveexec_b64 s[2:3], s[4:5]
	s_or_b64 exec, exec, s[2:3]
	v_add_f32_e32 v100, v190, v101
	v_mul_f32_e32 v100, 0xbfb8aa3b, v100
	v_exp_f32_e32 v100, v100
	s_nop 0
	v_add_f32_e32 v100, 1.0, v100
	v_rcp_f32_e32 v100, v100
	s_nop 0
	v_cvt_pk_bf16_f32 v180, v100, s0
	v_add_u32_e32 v100, -2, v116
	v_ashrrev_i32_e32 v101, 31, v100
	v_lshlrev_b64 v[176:177], 9, v[100:101]
	v_lshl_add_u64 v[104:105], v[184:185], 0, v[176:177]
	global_store_short v[104:105], v180, off sc0 sc1
	v_add_f32_e32 v104, v2, v106
	v_cmp_ngt_f32_e32 vcc, s74, v104
	v_xor_b32_e32 v106, 0x80000000, v104
	s_and_saveexec_b64 s[2:3], vcc
	s_xor_b64 s[4:5], exec, s[2:3]
	s_cbranch_execz .LBB0_256
	v_mul_f32_e32 v104, 0xbfb8aa3b, v104
	v_exp_f32_e32 v104, v104
	s_nop 0
	v_add_f32_e32 v104, 1.0, v104
	v_cmp_gt_f32_e32 vcc, s75, v104
	s_nop 1
	v_cndmask_b32_e64 v105, 0, 32, vcc
	v_ldexp_f32 v104, v104, v105
	v_log_f32_e32 v104, v104
	s_nop 0
	v_mul_f32_e32 v105, 0x3f317217, v104
	v_fma_f32 v105, v104, s88, -v105
	v_fmac_f32_e32 v105, 0x3377d1cf, v104
	v_fmac_f32_e32 v105, 0x3f317217, v104
	v_cmp_lt_f32_e64 s[2:3], |v104|, s70
	s_nop 1
	v_cndmask_b32_e64 v104, v104, v105, s[2:3]
	v_cndmask_b32_e32 v105, 0, v233, vcc
	v_sub_f32_e32 v106, v104, v105
.LBB0_256:
	s_andn2_saveexec_b64 s[2:3], s[4:5]
	s_or_b64 exec, exec, s[2:3]
	v_add_f32_e32 v102, v190, v102
	v_mul_f32_e32 v102, 0xbfb8aa3b, v102
	v_exp_f32_e32 v102, v102
	v_add_u32_e32 v104, -1, v116
	v_ashrrev_i32_e32 v105, 31, v104
	v_lshlrev_b64 v[180:181], 9, v[104:105]
	v_add_f32_e32 v102, 1.0, v102
	v_rcp_f32_e32 v102, v102
	v_add_f32_e32 v2, v2, v107
	v_lshl_add_u64 v[246:247], v[184:185], 0, v[180:181]
	v_cmp_ngt_f32_e32 vcc, s74, v2
	v_cvt_pk_bf16_f32 v102, v102, s0
	global_store_short v[246:247], v102, off sc0 sc1
	v_xor_b32_e32 v102, 0x80000000, v2
	s_and_saveexec_b64 s[2:3], vcc
	s_xor_b64 s[4:5], exec, s[2:3]
	s_cbranch_execz .LBB0_258
	v_mul_f32_e32 v2, 0xbfb8aa3b, v2
	v_exp_f32_e32 v2, v2
	s_nop 0
	v_add_f32_e32 v2, 1.0, v2
	v_cmp_gt_f32_e32 vcc, s75, v2
	s_nop 1
	v_cndmask_b32_e64 v102, 0, 32, vcc
	v_ldexp_f32 v2, v2, v102
	v_log_f32_e32 v2, v2
	s_nop 0
	v_mul_f32_e32 v102, 0x3f317217, v2
	v_fma_f32 v102, v2, s88, -v102
	v_fmac_f32_e32 v102, 0x3377d1cf, v2
	v_fmac_f32_e32 v102, 0x3f317217, v2
	v_cmp_lt_f32_e64 s[2:3], |v2|, s70
	s_nop 1
	v_cndmask_b32_e64 v2, v2, v102, s[2:3]
	v_cndmask_b32_e32 v102, 0, v233, vcc
	v_sub_f32_e32 v102, v2, v102
.LBB0_258:
	s_andn2_saveexec_b64 s[2:3], s[4:5]
	s_or_b64 exec, exec, s[2:3]
	v_sub_f32_e32 v2, -0.5, v106
	v_mul_f32_e32 v2, 0x3fb8aa3b, v2
	v_exp_f32_e32 v245, v2
	v_sub_f32_e32 v2, -0.5, v111
	v_mul_f32_e32 v2, 0x3fb8aa3b, v2
	v_exp_f32_e32 v111, v2
	v_sub_f32_e32 v2, -0.5, v110
	v_mul_f32_e32 v2, 0x3fb8aa3b, v2
	v_exp_f32_e32 v110, v2
	v_sub_f32_e32 v2, -0.5, v244
	v_mul_f32_e32 v2, 0x3fb8aa3b, v2
	v_exp_f32_e32 v244, v2
	v_sub_f32_e32 v2, -0.5, v215
	v_mul_f32_e32 v2, 0x3fb8aa3b, v2
	v_exp_f32_e32 v215, v2
	v_sub_f32_e32 v2, -0.5, v214
	v_mul_f32_e32 v2, 0x3fb8aa3b, v2
	v_exp_f32_e32 v214, v2
	v_sub_f32_e32 v2, -0.5, v213
	v_mul_f32_e32 v2, 0x3fb8aa3b, v2
	v_exp_f32_e32 v213, v2
	v_sub_f32_e32 v2, -0.5, v212
	v_mul_f32_e32 v2, 0x3fb8aa3b, v2
	v_exp_f32_e32 v212, v2
	v_sub_f32_e32 v2, -0.5, v211
	v_mul_f32_e32 v2, 0x3fb8aa3b, v2
	v_exp_f32_e32 v211, v2
	v_sub_f32_e32 v2, -0.5, v210
	v_mul_f32_e32 v2, 0x3fb8aa3b, v2
	v_exp_f32_e32 v210, v2
	v_sub_f32_e32 v2, -0.5, v209
	v_sub_f32_e32 v102, -0.5, v102
	v_mul_f32_e32 v2, 0x3fb8aa3b, v2
	v_mul_f32_e32 v102, 0x3fb8aa3b, v102
	v_exp_f32_e32 v209, v2
	v_sub_f32_e32 v2, -0.5, v208
	v_exp_f32_e32 v246, v102
	v_add_f32_e32 v102, v190, v103
	v_mul_f32_e32 v2, 0x3fb8aa3b, v2
	v_mul_f32_e32 v102, 0xbfb8aa3b, v102
	v_exp_f32_e32 v208, v2
	v_sub_f32_e32 v2, -0.5, v207
	v_exp_f32_e32 v102, v102
	v_mul_f32_e32 v2, 0x3fb8aa3b, v2
	v_exp_f32_e32 v207, v2
	v_sub_f32_e32 v2, -0.5, v206
	v_mul_f32_e32 v2, 0x3fb8aa3b, v2
	v_exp_f32_e32 v206, v2
	v_sub_f32_e32 v2, -0.5, v191
	v_add_f32_e32 v102, 1.0, v102
	v_mul_f32_e32 v2, 0x3fb8aa3b, v2
	v_rcp_f32_e32 v102, v102
	v_exp_f32_e32 v106, v2
	v_cmp_gt_u32_e64 s[4:5], 16, v117
	v_cmp_lt_u32_e64 s[2:3], 31, v117
	v_ashrrev_i32_e32 v117, 31, v116
	v_and_or_b32 v2, v234, 64, v183
	v_cmp_eq_u32_e32 vcc, 3, v182
	v_lshlrev_b64 v[182:183], 9, v[116:117]
	v_cvt_pk_bf16_f32 v107, v102, s0
	v_lshl_add_u64 v[102:103], v[184:185], 0, v[182:183]
	global_store_short v[102:103], v107, off sc0 sc1
	v_lshl_add_u64 v[102:103], v[0:1], 2, s[18:19]
	v_sub_f32_e64 v1, -v206, v106
	v_sub_f32_e64 v107, -v208, v207
	v_lshlrev_b32_e32 v2, 2, v2
	v_add_f32_e32 v1, v1, v107
	ds_bpermute_b32 v247, v2, v1
	ds_bpermute_b32 v248, v2, v1 offset:64
	ds_bpermute_b32 v249, v2, v1 offset:128
	v_lshlrev_b64 v[190:191], 10, v[120:121]
	ds_bpermute_b32 v1, v2, v1 offset:192
	s_waitcnt lgkmcnt(3)
	v_add_f32_e32 v107, 0, v247
	v_cndmask_b32_e64 v107, v107, 0, s[4:5]
	s_waitcnt lgkmcnt(2)
	v_cndmask_b32_e64 v184, 0, v248, s[2:3]
	v_add_f32_e32 v107, v107, v184
	s_waitcnt lgkmcnt(1)
	v_cndmask_b32_e32 v184, 0, v249, vcc
	v_add_f32_e32 v107, v107, v184
	v_sub_f32_e32 v184, v107, v106
	v_lshl_add_u64 v[106:107], v[102:103], 0, v[190:191]
	global_store_dword v[106:107], v184, off sc0 sc1
	v_sub_f32_e32 v120, v184, v206
	v_lshlrev_b64 v[184:185], 10, v[186:187]
	v_lshl_add_u64 v[106:107], v[102:103], 0, v[184:185]
	v_lshlrev_b64 v[186:187], 10, v[188:189]
	global_store_dword v[106:107], v120, off sc0 sc1
	v_sub_f32_e32 v120, v120, v207
	v_lshl_add_u64 v[106:107], v[102:103], 0, v[186:187]
	v_lshlrev_b64 v[188:189], 10, v[192:193]
	global_store_dword v[106:107], v120, off sc0 sc1
	v_sub_f32_e32 v120, v120, v208
	v_lshl_add_u64 v[106:107], v[102:103], 0, v[188:189]
	global_store_dword v[106:107], v120, off sc0 sc1
	v_add_f32_e32 v106, v247, v248
	s_waitcnt lgkmcnt(0)
	v_add_f32_e32 v1, v249, v1
	v_add_f32_e32 v1, v106, v1
	v_sub_f32_e64 v106, -v210, v209
	v_sub_f32_e64 v107, -v212, v211
	v_add_f32_e32 v106, v106, v107
	ds_bpermute_b32 v120, v2, v106
	ds_bpermute_b32 v121, v2, v106 offset:64
	ds_bpermute_b32 v206, v2, v106 offset:128
	v_add_f32_e32 v1, 0, v1
	ds_bpermute_b32 v207, v2, v106 offset:192
	s_waitcnt lgkmcnt(3)
	v_cndmask_b32_e64 v106, v120, 0, s[4:5]
	v_add_f32_e32 v106, v1, v106
	s_waitcnt lgkmcnt(2)
	v_cndmask_b32_e64 v107, 0, v121, s[2:3]
	v_add_f32_e32 v106, v106, v107
	s_waitcnt lgkmcnt(1)
	v_cndmask_b32_e32 v107, 0, v206, vcc
	v_add_f32_e32 v106, v106, v107
	v_lshlrev_b64 v[192:193], 10, v[194:195]
	v_sub_f32_e32 v208, v106, v209
	v_lshl_add_u64 v[106:107], v[102:103], 0, v[192:193]
	v_lshlrev_b64 v[194:195], 10, v[196:197]
	global_store_dword v[106:107], v208, off sc0 sc1
	v_sub_f32_e32 v208, v208, v210
	v_lshl_add_u64 v[106:107], v[102:103], 0, v[194:195]
	v_lshlrev_b64 v[196:197], 10, v[198:199]
	global_store_dword v[106:107], v208, off sc0 sc1
	v_sub_f32_e32 v208, v208, v211
	v_lshl_add_u64 v[106:107], v[102:103], 0, v[196:197]
	v_lshlrev_b64 v[198:199], 10, v[200:201]
	global_store_dword v[106:107], v208, off sc0 sc1
	v_sub_f32_e32 v208, v208, v212
	v_lshl_add_u64 v[106:107], v[102:103], 0, v[198:199]
	global_store_dword v[106:107], v208, off sc0 sc1
	v_add_f32_e32 v106, v120, v121
	s_waitcnt lgkmcnt(0)
	v_add_f32_e32 v107, v206, v207
	v_add_f32_e32 v106, v106, v107
	v_add_f32_e32 v1, v1, v106
	v_sub_f32_e64 v106, -v214, v213
	v_sub_f32_e64 v107, -v244, v215
	v_add_f32_e32 v106, v106, v107
	ds_bpermute_b32 v120, v2, v106
	ds_bpermute_b32 v121, v2, v106 offset:64
	ds_bpermute_b32 v208, v2, v106 offset:128
	ds_bpermute_b32 v209, v2, v106 offset:192
	v_lshlrev_b64 v[200:201], 10, v[202:203]
	s_waitcnt lgkmcnt(3)
	v_cndmask_b32_e64 v106, v120, 0, s[4:5]
	v_add_f32_e32 v106, v1, v106
	s_waitcnt lgkmcnt(2)
	v_cndmask_b32_e64 v107, 0, v121, s[2:3]
	v_add_f32_e32 v106, v106, v107
	s_waitcnt lgkmcnt(1)
	v_cndmask_b32_e32 v107, 0, v208, vcc
	v_add_f32_e32 v106, v106, v107
	v_sub_f32_e32 v206, v106, v213
	v_lshl_add_u64 v[106:107], v[102:103], 0, v[200:201]
	v_lshlrev_b64 v[202:203], 10, v[112:113]
	global_store_dword v[106:107], v206, off sc0 sc1
	v_sub_f32_e32 v206, v206, v214
	v_lshl_add_u64 v[106:107], v[102:103], 0, v[202:203]
	v_lshlrev_b64 v[204:205], 10, v[204:205]
	global_store_dword v[106:107], v206, off sc0 sc1
	v_sub_f32_e32 v112, v206, v215
	v_lshl_add_u64 v[106:107], v[102:103], 0, v[204:205]
	v_lshlrev_b64 v[206:207], 10, v[114:115]
	global_store_dword v[106:107], v112, off sc0 sc1
	v_sub_f32_e32 v112, v112, v244
	v_lshl_add_u64 v[106:107], v[102:103], 0, v[206:207]
	global_store_dword v[106:107], v112, off sc0 sc1
	v_add_f32_e32 v106, v120, v121
	s_waitcnt lgkmcnt(0)
	v_add_f32_e32 v107, v208, v209
	v_add_f32_e32 v106, v106, v107
	v_add_f32_e32 v1, v1, v106
	v_sub_f32_e64 v106, -v111, v110
	v_sub_f32_e64 v107, -v246, v245
	v_add_f32_e32 v106, v106, v107
	ds_bpermute_b32 v107, v2, v106
	ds_bpermute_b32 v112, v2, v106 offset:64
	ds_bpermute_b32 v106, v2, v106 offset:128
	v_lshlrev_b64 v[208:209], 10, v[108:109]
	v_lshlrev_b64 v[210:211], 10, v[100:101]
	s_waitcnt lgkmcnt(2)
	v_cndmask_b32_e64 v107, v107, 0, s[4:5]
	v_add_f32_e32 v1, v1, v107
	s_waitcnt lgkmcnt(1)
	v_cndmask_b32_e64 v107, 0, v112, s[2:3]
	v_add_f32_e32 v1, v1, v107
	s_waitcnt lgkmcnt(0)
	v_cndmask_b32_e32 v106, 0, v106, vcc
	v_add_f32_e32 v1, v1, v106
	v_sub_f32_e32 v1, v1, v110
	v_lshl_add_u64 v[106:107], v[102:103], 0, v[208:209]
	global_store_dword v[106:107], v1, off sc0 sc1
	v_sub_f32_e32 v1, v1, v111
	v_lshl_add_u64 v[100:101], v[102:103], 0, v[210:211]
	v_lshlrev_b64 v[212:213], 10, v[104:105]
	global_store_dword v[100:101], v1, off sc0 sc1
	v_sub_f32_e32 v1, v1, v245
	v_lshl_add_u64 v[100:101], v[102:103], 0, v[212:213]
	v_lshlrev_b64 v[214:215], 10, v[116:117]
	v_cvt_pk_bf16_f32 v113, v128, v129
	global_store_dword v[100:101], v1, off sc0 sc1
	v_lshl_add_u64 v[100:101], v[102:103], 0, v[214:215]
	v_lshlrev_b32_e32 v102, 16, v113
	v_and_b32_e32 v103, 0xffff0000, v113
	v_pk_add_f32 v[102:103], v[128:129], v[102:103] neg_lo:[0,1] neg_hi:[0,1]
	v_cvt_pk_bf16_f32 v114, v126, v127
	v_cvt_pk_bf16_f32 v105, v102, v103
	v_lshlrev_b32_e32 v102, 16, v114
	v_and_b32_e32 v103, 0xffff0000, v114
	v_cvt_pk_bf16_f32 v115, v124, v125
	v_sub_f32_e32 v1, v1, v246
	v_pk_add_f32 v[102:103], v[126:127], v[102:103] neg_lo:[0,1] neg_hi:[0,1]
	v_lshlrev_b32_e32 v126, 16, v115
	v_and_b32_e32 v127, 0xffff0000, v115
	global_store_dword v[100:101], v1, off sc0 sc1
	v_pk_add_f32 v[124:125], v[124:125], v[126:127] neg_lo:[0,1] neg_hi:[0,1]
	v_cvt_pk_bf16_f32 v116, v118, v119
	v_cvt_pk_bf16_f32 v107, v124, v125
	global_load_dword v125, v[140:141], off offset:64
	global_load_dword v124, v[136:137], off offset:64
	v_lshlrev_b32_e32 v100, 16, v116
	v_and_b32_e32 v101, 0xffff0000, v116
	v_pk_add_f32 v[100:101], v[118:119], v[100:101] neg_lo:[0,1] neg_hi:[0,1]
	v_cvt_pk_bf16_f32 v117, v122, v123
	v_cvt_pk_bf16_f32 v118, v134, v135
	v_cvt_pk_bf16_f32 v119, v132, v133
	v_cvt_pk_bf16_f32 v120, v100, v101
	v_lshlrev_b32_e32 v100, 16, v117
	v_mfma_f32_16x16x32_bf16 v[126:129], v[4:7], v[116:119], 0
	v_and_b32_e32 v101, 0xffff0000, v117
	v_pk_add_f32 v[100:101], v[122:123], v[100:101] neg_lo:[0,1] neg_hi:[0,1]
	v_cvt_pk_bf16_f32 v112, v130, v131
	v_cvt_pk_bf16_f32 v121, v100, v101
	v_lshlrev_b32_e32 v100, 16, v118
	v_and_b32_e32 v101, 0xffff0000, v118
	v_pk_add_f32 v[100:101], v[134:135], v[100:101] neg_lo:[0,1] neg_hi:[0,1]
	v_mfma_f32_16x16x32_bf16 v[20:23], v[20:23], v[116:119], v[126:129]
	v_cvt_pk_bf16_f32 v122, v100, v101
	v_lshlrev_b32_e32 v100, 16, v119
	v_and_b32_e32 v101, 0xffff0000, v119
	v_pk_add_f32 v[100:101], v[132:133], v[100:101] neg_lo:[0,1] neg_hi:[0,1]
	v_cvt_pk_bf16_f32 v108, v217, v224
	v_cvt_pk_bf16_f32 v123, v100, v101
	v_cvt_pk_bf16_f32 v109, v225, v243
	v_cvt_pk_bf16_f32 v110, v228, v242
	v_mfma_f32_16x16x32_bf16 v[4:7], v[4:7], v[120:123], v[20:23]
	v_cvt_pk_bf16_f32 v111, v226, v229
	v_lshlrev_b32_e32 v100, 16, v112
	v_and_b32_e32 v101, 0xffff0000, v112
	v_mfma_f32_16x16x32_bf16 v[4:7], v[12:15], v[112:115], v[4:7]
	v_add_f32_e64 v100, v130, -v100
	v_add_f32_e64 v101, v131, -v101
	v_cvt_pk_bf16_f32 v106, v102, v103
	v_cvt_pk_bf16_f32 v104, v100, v101
	v_mfma_f32_16x16x32_bf16 v[4:7], v[24:27], v[112:115], v[4:7]
	v_cvt_pk_bf16_f32 v100, v222, v227
	v_cvt_pk_bf16_f32 v101, v220, v223
	v_cvt_pk_bf16_f32 v102, v218, v221
	v_mfma_f32_16x16x32_bf16 v[20:23], v[8:11], v[108:111], 0
	v_cvt_pk_bf16_f32 v103, v216, v219
	v_mfma_f32_16x16x32_bf16 v[8:11], v[12:15], v[104:107], v[4:7]
	s_nop 0
	v_mfma_f32_16x16x32_bf16 v[4:7], v[16:19], v[100:103], v[20:23]
	s_waitcnt vmcnt(1)
	s_nop 4
	v_add_f32_e32 v1, v125, v8
	v_cmp_ngt_f32_e64 s[6:7], s74, v1
	v_xor_b32_e32 v12, 0x80000000, v1
	s_and_saveexec_b64 s[8:9], s[6:7]
	s_xor_b64 s[26:27], exec, s[8:9]
	s_cbranch_execz .LBB0_260
	v_mul_f32_e32 v1, 0xbfb8aa3b, v1
	v_exp_f32_e32 v1, v1
	s_nop 0
	v_add_f32_e32 v1, 1.0, v1
	v_cmp_gt_f32_e64 s[6:7], s75, v1
	s_nop 1
	v_cndmask_b32_e64 v8, 0, 32, s[6:7]
	v_ldexp_f32 v1, v1, v8
	v_log_f32_e32 v1, v1
	s_nop 0
	v_mul_f32_e32 v8, 0x3f317217, v1
	v_fma_f32 v8, v1, s88, -v8
	v_fmac_f32_e32 v8, 0x3377d1cf, v1
	v_fmac_f32_e32 v8, 0x3f317217, v1
	v_cmp_lt_f32_e64 s[8:9], |v1|, s70
	s_nop 1
	v_cndmask_b32_e64 v1, v1, v8, s[8:9]
	v_cndmask_b32_e64 v8, 0, v233, s[6:7]
	v_sub_f32_e32 v12, v1, v8
.LBB0_260:
	s_andn2_saveexec_b64 s[6:7], s[26:27]
	s_or_b64 exec, exec, s[6:7]
	s_waitcnt vmcnt(0)
	v_add_f32_e32 v1, v124, v4
	v_mul_f32_e32 v1, 0xbfb8aa3b, v1
	v_exp_f32_e32 v1, v1
	v_or_b32_e32 v0, 16, v0
	v_lshl_add_u64 v[14:15], s[20:21], 0, v[138:139]
	v_add_f32_e32 v4, v125, v9
	v_add_f32_e32 v1, 1.0, v1
	v_rcp_f32_e32 v13, v1
	v_ashrrev_i32_e32 v1, 31, v0
	v_lshl_add_u64 v[8:9], v[0:1], 1, v[14:15]
	v_cmp_ngt_f32_e64 s[6:7], s74, v4
	v_cvt_pk_bf16_f32 v13, v13, s0
	global_store_short v[8:9], v13, off sc0 sc1
	v_xor_b32_e32 v13, 0x80000000, v4
	s_and_saveexec_b64 s[8:9], s[6:7]
	s_xor_b64 s[26:27], exec, s[8:9]
	s_cbranch_execz .LBB0_262
	v_mul_f32_e32 v4, 0xbfb8aa3b, v4
	v_exp_f32_e32 v4, v4
	s_nop 0
	v_add_f32_e32 v4, 1.0, v4
	v_cmp_gt_f32_e64 s[6:7], s75, v4
	s_nop 1
	v_cndmask_b32_e64 v8, 0, 32, s[6:7]
	v_ldexp_f32 v4, v4, v8
	v_log_f32_e32 v4, v4
	s_nop 0
	v_mul_f32_e32 v8, 0x3f317217, v4
	v_fma_f32 v8, v4, s88, -v8
	v_fmac_f32_e32 v8, 0x3377d1cf, v4
	v_fmac_f32_e32 v8, 0x3f317217, v4
	v_cmp_lt_f32_e64 s[8:9], |v4|, s70
	s_nop 1
	v_cndmask_b32_e64 v4, v4, v8, s[8:9]
	v_cndmask_b32_e64 v8, 0, v233, s[6:7]
	v_sub_f32_e32 v13, v4, v8
.LBB0_262:
	s_andn2_saveexec_b64 s[6:7], s[26:27]
	s_or_b64 exec, exec, s[6:7]
	v_add_f32_e32 v4, v124, v5
	v_mul_f32_e32 v4, 0xbfb8aa3b, v4
	v_exp_f32_e32 v4, v4
	v_lshl_add_u64 v[8:9], s[20:21], 0, v[142:143]
	v_lshl_add_u64 v[8:9], v[0:1], 1, v[8:9]
	v_add_f32_e32 v4, 1.0, v4
	v_rcp_f32_e32 v5, v4
	v_add_f32_e32 v4, v125, v10
	v_cmp_ngt_f32_e64 s[6:7], s74, v4
	v_xor_b32_e32 v14, 0x80000000, v4
	v_cvt_pk_bf16_f32 v5, v5, s0
	global_store_short v[8:9], v5, off sc0 sc1
	s_and_saveexec_b64 s[8:9], s[6:7]
	s_xor_b64 s[26:27], exec, s[8:9]
	s_cbranch_execz .LBB0_264
	v_mul_f32_e32 v4, 0xbfb8aa3b, v4
	v_exp_f32_e32 v4, v4
	s_nop 0
	v_add_f32_e32 v4, 1.0, v4
	v_cmp_gt_f32_e64 s[6:7], s75, v4
	s_nop 1
	v_cndmask_b32_e64 v5, 0, 32, s[6:7]
	v_ldexp_f32 v4, v4, v5
	v_log_f32_e32 v4, v4
	s_nop 0
	v_mul_f32_e32 v5, 0x3f317217, v4
	v_fma_f32 v5, v4, s88, -v5
	v_fmac_f32_e32 v5, 0x3377d1cf, v4
	v_fmac_f32_e32 v5, 0x3f317217, v4
	v_cmp_lt_f32_e64 s[8:9], |v4|, s70
	s_nop 1
	v_cndmask_b32_e64 v4, v4, v5, s[8:9]
	v_cndmask_b32_e64 v5, 0, v233, s[6:7]
	v_sub_f32_e32 v14, v4, v5
.LBB0_264:
	s_andn2_saveexec_b64 s[6:7], s[26:27]
	s_or_b64 exec, exec, s[6:7]
	v_add_f32_e32 v4, v124, v6
	v_mul_f32_e32 v4, 0xbfb8aa3b, v4
	v_exp_f32_e32 v4, v4
	v_lshl_add_u64 v[8:9], s[20:21], 0, v[146:147]
	v_lshl_add_u64 v[8:9], v[0:1], 1, v[8:9]
	v_add_f32_e32 v4, 1.0, v4
	v_rcp_f32_e32 v5, v4
	v_add_f32_e32 v4, v125, v11
	v_cmp_ngt_f32_e64 s[6:7], s74, v4
	v_xor_b32_e32 v15, 0x80000000, v4
	v_cvt_pk_bf16_f32 v5, v5, s0
	global_store_short v[8:9], v5, off sc0 sc1
	s_and_saveexec_b64 s[8:9], s[6:7]
	s_xor_b64 s[26:27], exec, s[8:9]
	s_cbranch_execz .LBB0_266
	v_mul_f32_e32 v4, 0xbfb8aa3b, v4
	v_exp_f32_e32 v4, v4
	s_nop 0
	v_add_f32_e32 v4, 1.0, v4
	v_cmp_gt_f32_e64 s[6:7], s75, v4
	s_nop 1
	v_cndmask_b32_e64 v5, 0, 32, s[6:7]
	v_ldexp_f32 v4, v4, v5
	v_log_f32_e32 v4, v4
	s_nop 0
	v_mul_f32_e32 v5, 0x3f317217, v4
	v_fma_f32 v5, v4, s88, -v5
	v_fmac_f32_e32 v5, 0x3377d1cf, v4
	v_fmac_f32_e32 v5, 0x3f317217, v4
	v_cmp_lt_f32_e64 s[8:9], |v4|, s70
	s_nop 1
	v_cndmask_b32_e64 v4, v4, v5, s[8:9]
	v_cndmask_b32_e64 v5, 0, v233, s[6:7]
	v_sub_f32_e32 v15, v4, v5
.LBB0_266:
	s_andn2_saveexec_b64 s[6:7], s[26:27]
	s_or_b64 exec, exec, s[6:7]
	v_add_f32_e32 v4, v124, v7
	v_mul_f32_e32 v4, 0xbfb8aa3b, v4
	v_exp_f32_e32 v4, v4
	v_mfma_f32_16x16x32_bf16 v[16:19], v[32:35], v[108:111], 0
	v_add_f32_e32 v4, 1.0, v4
	v_rcp_f32_e32 v4, v4
	s_nop 0
	v_cvt_pk_bf16_f32 v6, v4, s0
	v_lshl_add_u64 v[4:5], s[20:21], 0, v[144:145]
	v_lshl_add_u64 v[4:5], v[0:1], 1, v[4:5]
	global_store_short v[4:5], v6, off sc0 sc1
	v_mfma_f32_16x16x32_bf16 v[4:7], v[40:43], v[116:119], 0
	v_mfma_f32_16x16x32_bf16 v[4:7], v[44:47], v[116:119], v[4:7]
	v_mfma_f32_16x16x32_bf16 v[4:7], v[40:43], v[120:123], v[4:7]
	v_mfma_f32_16x16x32_bf16 v[4:7], v[28:31], v[112:115], v[4:7]
	v_mfma_f32_16x16x32_bf16 v[4:7], v[48:51], v[112:115], v[4:7]
	v_mfma_f32_16x16x32_bf16 v[8:11], v[28:31], v[104:107], v[4:7]
	v_mfma_f32_16x16x32_bf16 v[4:7], v[36:39], v[100:103], v[16:19]
	s_nop 6
	v_add_f32_e32 v8, v125, v8
	v_cmp_ngt_f32_e64 s[6:7], s74, v8
	v_xor_b32_e32 v16, 0x80000000, v8
	s_and_saveexec_b64 s[8:9], s[6:7]
	s_xor_b64 s[26:27], exec, s[8:9]
	s_cbranch_execz .LBB0_268
	v_mul_f32_e32 v8, 0xbfb8aa3b, v8
	v_exp_f32_e32 v8, v8
	s_nop 0
	v_add_f32_e32 v8, 1.0, v8
	v_cmp_gt_f32_e64 s[6:7], s75, v8
	s_nop 1
	v_cndmask_b32_e64 v16, 0, 32, s[6:7]
	v_ldexp_f32 v8, v8, v16
	v_log_f32_e32 v8, v8
	s_nop 0
	v_mul_f32_e32 v16, 0x3f317217, v8
	v_fma_f32 v16, v8, s88, -v16
	v_fmac_f32_e32 v16, 0x3377d1cf, v8
	v_fmac_f32_e32 v16, 0x3f317217, v8
	v_cmp_lt_f32_e64 s[8:9], |v8|, s70
	s_nop 1
	v_cndmask_b32_e64 v8, v8, v16, s[8:9]
	v_cndmask_b32_e64 v16, 0, v233, s[6:7]
	v_sub_f32_e32 v16, v8, v16
.LBB0_268:
	s_andn2_saveexec_b64 s[6:7], s[26:27]
	s_or_b64 exec, exec, s[6:7]
	v_add_f32_e32 v4, v124, v4
	v_mul_f32_e32 v4, 0xbfb8aa3b, v4
	v_exp_f32_e32 v4, v4
	v_lshl_add_u64 v[18:19], s[20:21], 0, v[148:149]
	v_add_f32_e32 v4, 1.0, v4
	v_rcp_f32_e32 v17, v4
	v_add_f32_e32 v4, v125, v9
	v_lshl_add_u64 v[8:9], v[0:1], 1, v[18:19]
	v_cmp_ngt_f32_e64 s[6:7], s74, v4
	v_cvt_pk_bf16_f32 v17, v17, s0
	global_store_short v[8:9], v17, off sc0 sc1
	v_xor_b32_e32 v17, 0x80000000, v4
	s_and_saveexec_b64 s[8:9], s[6:7]
	s_xor_b64 s[26:27], exec, s[8:9]
	s_cbranch_execz .LBB0_270
	v_mul_f32_e32 v4, 0xbfb8aa3b, v4
	v_exp_f32_e32 v4, v4
	s_nop 0
	v_add_f32_e32 v4, 1.0, v4
	v_cmp_gt_f32_e64 s[6:7], s75, v4
	s_nop 1
	v_cndmask_b32_e64 v8, 0, 32, s[6:7]
	v_ldexp_f32 v4, v4, v8
	v_log_f32_e32 v4, v4
	s_nop 0
	v_mul_f32_e32 v8, 0x3f317217, v4
	v_fma_f32 v8, v4, s88, -v8
	v_fmac_f32_e32 v8, 0x3377d1cf, v4
	v_fmac_f32_e32 v8, 0x3f317217, v4
	v_cmp_lt_f32_e64 s[8:9], |v4|, s70
	s_nop 1
	v_cndmask_b32_e64 v4, v4, v8, s[8:9]
	v_cndmask_b32_e64 v8, 0, v233, s[6:7]
	v_sub_f32_e32 v17, v4, v8
.LBB0_270:
	s_andn2_saveexec_b64 s[6:7], s[26:27]
	s_or_b64 exec, exec, s[6:7]
	v_add_f32_e32 v4, v124, v5
	v_mul_f32_e32 v4, 0xbfb8aa3b, v4
	v_exp_f32_e32 v4, v4
	v_lshl_add_u64 v[8:9], s[20:21], 0, v[150:151]
	v_lshl_add_u64 v[8:9], v[0:1], 1, v[8:9]
	v_add_f32_e32 v4, 1.0, v4
	v_rcp_f32_e32 v5, v4
	v_add_f32_e32 v4, v125, v10
	v_cmp_ngt_f32_e64 s[6:7], s74, v4
	v_xor_b32_e32 v18, 0x80000000, v4
	v_cvt_pk_bf16_f32 v5, v5, s0
	global_store_short v[8:9], v5, off sc0 sc1
	s_and_saveexec_b64 s[8:9], s[6:7]
	s_xor_b64 s[26:27], exec, s[8:9]
	s_cbranch_execz .LBB0_272
	v_mul_f32_e32 v4, 0xbfb8aa3b, v4
	v_exp_f32_e32 v4, v4
	s_nop 0
	v_add_f32_e32 v4, 1.0, v4
	v_cmp_gt_f32_e64 s[6:7], s75, v4
	s_nop 1
	v_cndmask_b32_e64 v5, 0, 32, s[6:7]
	v_ldexp_f32 v4, v4, v5
	v_log_f32_e32 v4, v4
	s_nop 0
	v_mul_f32_e32 v5, 0x3f317217, v4
	v_fma_f32 v5, v4, s88, -v5
	v_fmac_f32_e32 v5, 0x3377d1cf, v4
	v_fmac_f32_e32 v5, 0x3f317217, v4
	v_cmp_lt_f32_e64 s[8:9], |v4|, s70
	s_nop 1
	v_cndmask_b32_e64 v4, v4, v5, s[8:9]
	v_cndmask_b32_e64 v5, 0, v233, s[6:7]
	v_sub_f32_e32 v18, v4, v5
.LBB0_272:
	s_andn2_saveexec_b64 s[6:7], s[26:27]
	s_or_b64 exec, exec, s[6:7]
	v_add_f32_e32 v4, v124, v6
	v_mul_f32_e32 v4, 0xbfb8aa3b, v4
	v_exp_f32_e32 v4, v4
	v_lshl_add_u64 v[8:9], s[20:21], 0, v[154:155]
	v_lshl_add_u64 v[8:9], v[0:1], 1, v[8:9]
	v_add_f32_e32 v4, 1.0, v4
	v_rcp_f32_e32 v5, v4
	v_add_f32_e32 v4, v125, v11
	v_cmp_ngt_f32_e64 s[6:7], s74, v4
	v_xor_b32_e32 v19, 0x80000000, v4
	v_cvt_pk_bf16_f32 v5, v5, s0
	global_store_short v[8:9], v5, off sc0 sc1
	s_and_saveexec_b64 s[8:9], s[6:7]
	s_xor_b64 s[26:27], exec, s[8:9]
	s_cbranch_execz .LBB0_274
	v_mul_f32_e32 v4, 0xbfb8aa3b, v4
	v_exp_f32_e32 v4, v4
	s_nop 0
	v_add_f32_e32 v4, 1.0, v4
	v_cmp_gt_f32_e64 s[6:7], s75, v4
	s_nop 1
	v_cndmask_b32_e64 v5, 0, 32, s[6:7]
	v_ldexp_f32 v4, v4, v5
	v_log_f32_e32 v4, v4
	s_nop 0
	v_mul_f32_e32 v5, 0x3f317217, v4
	v_fma_f32 v5, v4, s88, -v5
	v_fmac_f32_e32 v5, 0x3377d1cf, v4
	v_fmac_f32_e32 v5, 0x3f317217, v4
	v_cmp_lt_f32_e64 s[8:9], |v4|, s70
	s_nop 1
	v_cndmask_b32_e64 v4, v4, v5, s[8:9]
	v_cndmask_b32_e64 v5, 0, v233, s[6:7]
	v_sub_f32_e32 v19, v4, v5
.LBB0_274:
	s_andn2_saveexec_b64 s[6:7], s[26:27]
	s_or_b64 exec, exec, s[6:7]
	v_add_f32_e32 v4, v124, v7
	v_mul_f32_e32 v4, 0xbfb8aa3b, v4
	v_exp_f32_e32 v4, v4
	v_mfma_f32_16x16x32_bf16 v[20:23], v[56:59], v[108:111], 0
	v_add_f32_e32 v4, 1.0, v4
	v_rcp_f32_e32 v4, v4
	s_nop 0
	v_cvt_pk_bf16_f32 v6, v4, s0
	v_lshl_add_u64 v[4:5], s[20:21], 0, v[152:153]
	v_lshl_add_u64 v[4:5], v[0:1], 1, v[4:5]
	global_store_short v[4:5], v6, off sc0 sc1
	v_mfma_f32_16x16x32_bf16 v[4:7], v[64:67], v[116:119], 0
	v_mfma_f32_16x16x32_bf16 v[4:7], v[68:71], v[116:119], v[4:7]
	v_mfma_f32_16x16x32_bf16 v[4:7], v[64:67], v[120:123], v[4:7]
	v_mfma_f32_16x16x32_bf16 v[4:7], v[52:55], v[112:115], v[4:7]
	v_mfma_f32_16x16x32_bf16 v[4:7], v[72:75], v[112:115], v[4:7]
	v_mfma_f32_16x16x32_bf16 v[8:11], v[52:55], v[104:107], v[4:7]
	v_mfma_f32_16x16x32_bf16 v[4:7], v[60:63], v[100:103], v[20:23]
	s_nop 6
	v_add_f32_e32 v8, v125, v8
	v_cmp_ngt_f32_e64 s[6:7], s74, v8
	v_xor_b32_e32 v20, 0x80000000, v8
	s_and_saveexec_b64 s[8:9], s[6:7]
	s_xor_b64 s[26:27], exec, s[8:9]
	s_cbranch_execz .LBB0_276
	v_mul_f32_e32 v8, 0xbfb8aa3b, v8
	v_exp_f32_e32 v8, v8
	s_nop 0
	v_add_f32_e32 v8, 1.0, v8
	v_cmp_gt_f32_e64 s[6:7], s75, v8
	s_nop 1
	v_cndmask_b32_e64 v20, 0, 32, s[6:7]
	v_ldexp_f32 v8, v8, v20
	v_log_f32_e32 v8, v8
	s_nop 0
	v_mul_f32_e32 v20, 0x3f317217, v8
	v_fma_f32 v20, v8, s88, -v20
	v_fmac_f32_e32 v20, 0x3377d1cf, v8
	v_fmac_f32_e32 v20, 0x3f317217, v8
	v_cmp_lt_f32_e64 s[8:9], |v8|, s70
	s_nop 1
	v_cndmask_b32_e64 v8, v8, v20, s[8:9]
	v_cndmask_b32_e64 v20, 0, v233, s[6:7]
	v_sub_f32_e32 v20, v8, v20
.LBB0_276:
	s_andn2_saveexec_b64 s[6:7], s[26:27]
	s_or_b64 exec, exec, s[6:7]
	v_add_f32_e32 v4, v124, v4
	v_mul_f32_e32 v4, 0xbfb8aa3b, v4
	v_exp_f32_e32 v4, v4
	v_lshl_add_u64 v[22:23], s[20:21], 0, v[168:169]
	v_add_f32_e32 v4, 1.0, v4
	v_rcp_f32_e32 v21, v4
	v_add_f32_e32 v4, v125, v9
	v_lshl_add_u64 v[8:9], v[0:1], 1, v[22:23]
	v_cmp_ngt_f32_e64 s[6:7], s74, v4
	v_cvt_pk_bf16_f32 v21, v21, s0
	global_store_short v[8:9], v21, off sc0 sc1
	v_xor_b32_e32 v21, 0x80000000, v4
	s_and_saveexec_b64 s[8:9], s[6:7]
	s_xor_b64 s[26:27], exec, s[8:9]
	s_cbranch_execz .LBB0_278
	v_mul_f32_e32 v4, 0xbfb8aa3b, v4
	v_exp_f32_e32 v4, v4
	s_nop 0
	v_add_f32_e32 v4, 1.0, v4
	v_cmp_gt_f32_e64 s[6:7], s75, v4
	s_nop 1
	v_cndmask_b32_e64 v8, 0, 32, s[6:7]
	v_ldexp_f32 v4, v4, v8
	v_log_f32_e32 v4, v4
	s_nop 0
	v_mul_f32_e32 v8, 0x3f317217, v4
	v_fma_f32 v8, v4, s88, -v8
	v_fmac_f32_e32 v8, 0x3377d1cf, v4
	v_fmac_f32_e32 v8, 0x3f317217, v4
	v_cmp_lt_f32_e64 s[8:9], |v4|, s70
	s_nop 1
	v_cndmask_b32_e64 v4, v4, v8, s[8:9]
	v_cndmask_b32_e64 v8, 0, v233, s[6:7]
	v_sub_f32_e32 v21, v4, v8
.LBB0_278:
	s_andn2_saveexec_b64 s[6:7], s[26:27]
	s_or_b64 exec, exec, s[6:7]
	v_add_f32_e32 v4, v124, v5
	v_mul_f32_e32 v4, 0xbfb8aa3b, v4
	v_exp_f32_e32 v4, v4
	v_lshl_add_u64 v[8:9], s[20:21], 0, v[170:171]
	v_lshl_add_u64 v[8:9], v[0:1], 1, v[8:9]
	v_add_f32_e32 v4, 1.0, v4
	v_rcp_f32_e32 v5, v4
	v_add_f32_e32 v4, v125, v10
	v_cmp_ngt_f32_e64 s[6:7], s74, v4
	v_xor_b32_e32 v22, 0x80000000, v4
	v_cvt_pk_bf16_f32 v5, v5, s0
	global_store_short v[8:9], v5, off sc0 sc1
	s_and_saveexec_b64 s[8:9], s[6:7]
	s_xor_b64 s[26:27], exec, s[8:9]
	s_cbranch_execz .LBB0_280
	v_mul_f32_e32 v4, 0xbfb8aa3b, v4
	v_exp_f32_e32 v4, v4
	s_nop 0
	v_add_f32_e32 v4, 1.0, v4
	v_cmp_gt_f32_e64 s[6:7], s75, v4
	s_nop 1
	v_cndmask_b32_e64 v5, 0, 32, s[6:7]
	v_ldexp_f32 v4, v4, v5
	v_log_f32_e32 v4, v4
	s_nop 0
	v_mul_f32_e32 v5, 0x3f317217, v4
	v_fma_f32 v5, v4, s88, -v5
	v_fmac_f32_e32 v5, 0x3377d1cf, v4
	v_fmac_f32_e32 v5, 0x3f317217, v4
	v_cmp_lt_f32_e64 s[8:9], |v4|, s70
	s_nop 1
	v_cndmask_b32_e64 v4, v4, v5, s[8:9]
	v_cndmask_b32_e64 v5, 0, v233, s[6:7]
	v_sub_f32_e32 v22, v4, v5
.LBB0_280:
	s_andn2_saveexec_b64 s[6:7], s[26:27]
	s_or_b64 exec, exec, s[6:7]
	v_add_f32_e32 v4, v124, v6
	v_mul_f32_e32 v4, 0xbfb8aa3b, v4
	v_exp_f32_e32 v4, v4
	v_lshl_add_u64 v[8:9], s[20:21], 0, v[172:173]
	v_lshl_add_u64 v[8:9], v[0:1], 1, v[8:9]
	v_add_f32_e32 v4, 1.0, v4
	v_rcp_f32_e32 v5, v4
	v_add_f32_e32 v4, v125, v11
	v_cmp_ngt_f32_e64 s[6:7], s74, v4
	v_xor_b32_e32 v23, 0x80000000, v4
	v_cvt_pk_bf16_f32 v5, v5, s0
	global_store_short v[8:9], v5, off sc0 sc1
	s_and_saveexec_b64 s[8:9], s[6:7]
	s_xor_b64 s[26:27], exec, s[8:9]
	s_cbranch_execz .LBB0_282
	v_mul_f32_e32 v4, 0xbfb8aa3b, v4
	v_exp_f32_e32 v4, v4
	s_nop 0
	v_add_f32_e32 v4, 1.0, v4
	v_cmp_gt_f32_e64 s[6:7], s75, v4
	s_nop 1
	v_cndmask_b32_e64 v5, 0, 32, s[6:7]
	v_ldexp_f32 v4, v4, v5
	v_log_f32_e32 v4, v4
	s_nop 0
	v_mul_f32_e32 v5, 0x3f317217, v4
	v_fma_f32 v5, v4, s88, -v5
	v_fmac_f32_e32 v5, 0x3377d1cf, v4
	v_fmac_f32_e32 v5, 0x3f317217, v4
	v_cmp_lt_f32_e64 s[8:9], |v4|, s70
	s_nop 1
	v_cndmask_b32_e64 v4, v4, v5, s[8:9]
	v_cndmask_b32_e64 v5, 0, v233, s[6:7]
	v_sub_f32_e32 v23, v4, v5
.LBB0_282:
	s_andn2_saveexec_b64 s[6:7], s[26:27]
	s_or_b64 exec, exec, s[6:7]
	v_add_f32_e32 v4, v124, v7
	v_mul_f32_e32 v4, 0xbfb8aa3b, v4
	v_exp_f32_e32 v4, v4
	v_mfma_f32_16x16x32_bf16 v[24:27], v[80:83], v[108:111], 0
	v_add_f32_e32 v4, 1.0, v4
	v_rcp_f32_e32 v4, v4
	s_nop 0
	v_cvt_pk_bf16_f32 v6, v4, s0
	v_lshl_add_u64 v[4:5], s[20:21], 0, v[178:179]
	v_lshl_add_u64 v[4:5], v[0:1], 1, v[4:5]
	global_store_short v[4:5], v6, off sc0 sc1
	v_mfma_f32_16x16x32_bf16 v[4:7], v[84:87], v[116:119], 0
	v_mfma_f32_16x16x32_bf16 v[4:7], v[92:95], v[116:119], v[4:7]
	v_mfma_f32_16x16x32_bf16 v[4:7], v[84:87], v[120:123], v[4:7]
	v_mfma_f32_16x16x32_bf16 v[4:7], v[76:79], v[112:115], v[4:7]
	v_mfma_f32_16x16x32_bf16 v[4:7], v[88:91], v[112:115], v[4:7]
	v_mfma_f32_16x16x32_bf16 v[8:11], v[76:79], v[104:107], v[4:7]
	v_mfma_f32_16x16x32_bf16 v[4:7], v[96:99], v[100:103], v[24:27]
	s_nop 6
	v_add_f32_e32 v24, v125, v8
	v_cmp_ngt_f32_e64 s[6:7], s74, v24
	v_xor_b32_e32 v8, 0x80000000, v24
	s_and_saveexec_b64 s[8:9], s[6:7]
	s_xor_b64 s[26:27], exec, s[8:9]
	s_cbranch_execz .LBB0_284
	v_mul_f32_e32 v8, 0xbfb8aa3b, v24
	v_exp_f32_e32 v8, v8
	s_nop 0
	v_add_f32_e32 v8, 1.0, v8
	v_cmp_gt_f32_e64 s[6:7], s75, v8
	s_nop 1
	v_cndmask_b32_e64 v24, 0, 32, s[6:7]
	v_ldexp_f32 v8, v8, v24
	v_log_f32_e32 v8, v8
	s_nop 0
	v_mul_f32_e32 v24, 0x3f317217, v8
	v_fma_f32 v24, v8, s88, -v24
	v_fmac_f32_e32 v24, 0x3377d1cf, v8
	v_fmac_f32_e32 v24, 0x3f317217, v8
	v_cmp_lt_f32_e64 s[8:9], |v8|, s70
	s_nop 1
	v_cndmask_b32_e64 v8, v8, v24, s[8:9]
	v_cndmask_b32_e64 v24, 0, v233, s[6:7]
	v_sub_f32_e32 v8, v8, v24
.LBB0_284:
	s_andn2_saveexec_b64 s[6:7], s[26:27]
	s_or_b64 exec, exec, s[6:7]
	v_add_f32_e32 v4, v124, v4
	v_mul_f32_e32 v4, 0xbfb8aa3b, v4
	v_exp_f32_e32 v4, v4
	v_lshl_add_u64 v[24:25], s[20:21], 0, v[174:175]
	v_add_f32_e32 v9, v125, v9
	v_lshl_add_u64 v[24:25], v[0:1], 1, v[24:25]
	v_add_f32_e32 v4, 1.0, v4
	v_rcp_f32_e32 v4, v4
	v_cmp_ngt_f32_e64 s[6:7], s74, v9
	v_cvt_pk_bf16_f32 v4, v4, s0
	global_store_short v[24:25], v4, off sc0 sc1
	v_xor_b32_e32 v4, 0x80000000, v9
	s_and_saveexec_b64 s[8:9], s[6:7]
	s_xor_b64 s[26:27], exec, s[8:9]
	s_cbranch_execz .LBB0_286
	v_mul_f32_e32 v4, 0xbfb8aa3b, v9
	v_exp_f32_e32 v4, v4
	s_nop 0
	v_add_f32_e32 v4, 1.0, v4
	v_cmp_gt_f32_e64 s[6:7], s75, v4
	s_nop 1
	v_cndmask_b32_e64 v9, 0, 32, s[6:7]
	v_ldexp_f32 v4, v4, v9
	v_log_f32_e32 v4, v4
	s_nop 0
	v_mul_f32_e32 v9, 0x3f317217, v4
	v_fma_f32 v9, v4, s88, -v9
	v_fmac_f32_e32 v9, 0x3377d1cf, v4
	v_fmac_f32_e32 v9, 0x3f317217, v4
	v_cmp_lt_f32_e64 s[8:9], |v4|, s70
	s_nop 1
	v_cndmask_b32_e64 v4, v4, v9, s[8:9]
	v_cndmask_b32_e64 v9, 0, v233, s[6:7]
	v_sub_f32_e32 v4, v4, v9
.LBB0_286:
	s_andn2_saveexec_b64 s[6:7], s[26:27]
	s_or_b64 exec, exec, s[6:7]
	v_add_f32_e32 v5, v124, v5
	v_mul_f32_e32 v5, 0xbfb8aa3b, v5
	v_exp_f32_e32 v5, v5
	v_lshl_add_u64 v[24:25], s[20:21], 0, v[176:177]
	v_add_f32_e32 v9, v125, v10
	v_lshl_add_u64 v[24:25], v[0:1], 1, v[24:25]
	v_add_f32_e32 v5, 1.0, v5
	v_rcp_f32_e32 v5, v5
	v_cmp_ngt_f32_e64 s[6:7], s74, v9
	v_cvt_pk_bf16_f32 v5, v5, s0
	global_store_short v[24:25], v5, off sc0 sc1
	v_xor_b32_e32 v5, 0x80000000, v9
	s_and_saveexec_b64 s[8:9], s[6:7]
	s_xor_b64 s[26:27], exec, s[8:9]
	s_cbranch_execz .LBB0_288
	v_mul_f32_e32 v5, 0xbfb8aa3b, v9
	v_exp_f32_e32 v5, v5
	s_nop 0
	v_add_f32_e32 v5, 1.0, v5
	v_cmp_gt_f32_e64 s[6:7], s75, v5
	s_nop 1
	v_cndmask_b32_e64 v9, 0, 32, s[6:7]
	v_ldexp_f32 v5, v5, v9
	v_log_f32_e32 v5, v5
	s_nop 0
	v_mul_f32_e32 v9, 0x3f317217, v5
	v_fma_f32 v9, v5, s88, -v9
	v_fmac_f32_e32 v9, 0x3377d1cf, v5
	v_fmac_f32_e32 v9, 0x3f317217, v5
	v_cmp_lt_f32_e64 s[8:9], |v5|, s70
	s_nop 1
	v_cndmask_b32_e64 v5, v5, v9, s[8:9]
	v_cndmask_b32_e64 v9, 0, v233, s[6:7]
	v_sub_f32_e32 v5, v5, v9
.LBB0_288:
	s_andn2_saveexec_b64 s[6:7], s[26:27]
	s_or_b64 exec, exec, s[6:7]
	v_add_f32_e32 v6, v124, v6
	v_mul_f32_e32 v6, 0xbfb8aa3b, v6
	v_exp_f32_e32 v6, v6
	v_lshl_add_u64 v[24:25], s[20:21], 0, v[180:181]
	v_add_f32_e32 v9, v125, v11
	v_lshl_add_u64 v[10:11], v[0:1], 1, v[24:25]
	v_add_f32_e32 v6, 1.0, v6
	v_rcp_f32_e32 v6, v6
	v_cmp_ngt_f32_e64 s[6:7], s74, v9
	v_cvt_pk_bf16_f32 v6, v6, s0
	global_store_short v[10:11], v6, off sc0 sc1
	v_xor_b32_e32 v6, 0x80000000, v9
	s_and_saveexec_b64 s[8:9], s[6:7]
	s_xor_b64 s[26:27], exec, s[8:9]
	s_cbranch_execz .LBB0_225
	v_mul_f32_e32 v6, 0xbfb8aa3b, v9
	v_exp_f32_e32 v6, v6
	s_nop 0
	v_add_f32_e32 v6, 1.0, v6
	v_cmp_gt_f32_e64 s[6:7], s75, v6
	s_nop 1
	v_cndmask_b32_e64 v9, 0, 32, s[6:7]
	v_ldexp_f32 v6, v6, v9
	v_log_f32_e32 v6, v6
	s_nop 0
	v_mul_f32_e32 v9, 0x3f317217, v6
	v_fma_f32 v9, v6, s88, -v9
	v_fmac_f32_e32 v9, 0x3377d1cf, v6
	v_fmac_f32_e32 v9, 0x3f317217, v6
	v_cmp_lt_f32_e64 s[8:9], |v6|, s70
	s_nop 1
	v_cndmask_b32_e64 v6, v6, v9, s[8:9]
	v_cndmask_b32_e64 v9, 0, v233, s[6:7]
	v_sub_f32_e32 v6, v6, v9
	s_branch .LBB0_225
